# p5epi + B cleanup + same dead-slot cleanup in C/A/M attention loops
# speedup vs baseline: 1.0002x; 1.0002x over previous
.LBB0_523:
	v_readlane_b32 vcc_lo, v254, 13
	v_readlane_b32 vcc_hi, v254, 14
	v_cndmask_b32_e64 v49, v17, v208, s[2:3]
	v_cndmask_b32_e64 v48, v16, v208, s[2:3]
	v_cndmask_b32_e64 v47, v15, v208, s[2:3]
	v_cndmask_b32_e64 v46, v14, v208, s[2:3]
	v_cndmask_b32_e64 v45, v13, v208, s[2:3]
	v_cndmask_b32_e64 v44, v12, v208, s[2:3]
	v_cndmask_b32_e64 v43, v11, v208, s[2:3]
	v_cndmask_b32_e64 v42, v10, v208, s[2:3]
	v_cndmask_b32_e64 v41, v9, v208, s[2:3]
	v_cndmask_b32_e64 v40, v8, v208, s[2:3]
	v_cndmask_b32_e64 v39, v7, v208, s[2:3]
	v_cndmask_b32_e64 v38, v6, v208, s[2:3]
	v_cndmask_b32_e64 v37, v5, v208, s[2:3]
	v_cndmask_b32_e64 v36, v4, v208, s[2:3]
	v_cndmask_b32_e64 v35, v3, v208, s[2:3]
	v_cndmask_b32_e64 v34, v2, v208, s[2:3]
	v_readlane_b32 s2, v255, 14
	s_and_b64 vcc, vcc, s[20:21]
	s_or_b32 s2, s2, s40
	s_cmp_lg_u32 s2, 0
	v_cndmask_b32_e32 v65, v33, v208, vcc
	v_cndmask_b32_e32 v64, v32, v208, vcc
	v_cndmask_b32_e32 v63, v31, v208, vcc
	v_cndmask_b32_e32 v62, v30, v208, vcc
	v_cndmask_b32_e32 v61, v29, v208, vcc
	v_cndmask_b32_e32 v60, v28, v208, vcc
	v_cndmask_b32_e32 v59, v27, v208, vcc
	v_cndmask_b32_e32 v58, v26, v208, vcc
	v_cndmask_b32_e32 v57, v25, v208, vcc
	v_cndmask_b32_e32 v56, v24, v208, vcc
	v_cndmask_b32_e32 v55, v23, v208, vcc
	v_cndmask_b32_e32 v54, v22, v208, vcc
	v_cndmask_b32_e32 v53, v21, v208, vcc
	v_cndmask_b32_e32 v52, v20, v208, vcc
	v_cndmask_b32_e32 v51, v19, v208, vcc
	v_cndmask_b32_e32 v50, v18, v208, vcc
	s_cselect_b64 vcc, -1, 0
	v_cndmask_b32_e32 v33, v208, v113, vcc
	v_cndmask_b32_e32 v32, v208, v112, vcc
	v_cndmask_b32_e32 v31, v208, v111, vcc
	v_cndmask_b32_e32 v30, v208, v110, vcc
	v_cndmask_b32_e32 v29, v208, v109, vcc
	v_cndmask_b32_e32 v28, v208, v108, vcc
	v_cndmask_b32_e32 v27, v208, v107, vcc
	v_cndmask_b32_e32 v26, v208, v106, vcc
	v_cndmask_b32_e32 v25, v208, v105, vcc
	v_cndmask_b32_e32 v24, v208, v104, vcc
	v_cndmask_b32_e32 v23, v208, v103, vcc
	v_cndmask_b32_e32 v22, v208, v102, vcc
	v_cndmask_b32_e32 v21, v208, v101, vcc
	v_cndmask_b32_e32 v20, v208, v100, vcc
	v_cndmask_b32_e32 v19, v208, v99, vcc
	v_cndmask_b32_e32 v18, v208, v98, vcc
	v_cndmask_b32_e64 v2, v82, v208, s[74:75]
	v_cndmask_b32_e64 v3, v208, v83, s[4:5]
	v_cndmask_b32_e64 v4, v84, v208, s[76:77]
	v_cndmask_b32_e64 v5, v85, v208, s[78:79]
	v_cndmask_b32_e64 v6, v86, v208, s[80:81]
	v_cndmask_b32_e64 v7, v87, v208, s[82:83]
	v_cndmask_b32_e64 v8, v88, v208, s[84:85]
	v_cndmask_b32_e64 v9, v89, v208, s[86:87]
	v_cndmask_b32_e64 v10, v90, v208, s[88:89]
	v_cndmask_b32_e64 v11, v91, v208, s[90:91]
	v_cndmask_b32_e64 v12, v92, v208, s[92:93]
	v_cndmask_b32_e64 v13, v93, v208, s[94:95]
	v_cndmask_b32_e64 v14, v94, v208, s[96:97]
	v_cndmask_b32_e64 v15, v95, v208, s[6:7]
	v_cndmask_b32_e64 v16, v96, v208, s[8:9]
	v_cndmask_b32_e64 v17, v97, v208, s[10:11]
	s_nop 12
	s_nop 0
	v_max3_f32 v0, v208, v66, v67
	v_max3_f32 v0, v0, v68, v69
	v_max3_f32 v0, v0, v70, v71
	v_max3_f32 v0, v0, v72, v73
	v_max3_f32 v0, v0, v74, v75
	v_max3_f32 v0, v0, v76, v77
	v_max3_f32 v0, v0, v78, v79
	v_max3_f32 v0, v0, v80, v81
	v_max3_f32 v0, v0, v50, v51
	v_max3_f32 v0, v0, v52, v53
	v_max3_f32 v0, v0, v54, v55
	v_max3_f32 v0, v0, v56, v57
	v_max3_f32 v0, v0, v58, v59
	v_max3_f32 v0, v0, v60, v61
	v_max3_f32 v0, v0, v62, v63
	v_max3_f32 v0, v0, v64, v65
	v_max3_f32 v0, v0, v34, v35
	v_max3_f32 v0, v0, v36, v37
	v_max3_f32 v0, v0, v38, v39
	v_max3_f32 v0, v0, v40, v41
	v_max3_f32 v0, v0, v42, v43
	v_max3_f32 v0, v0, v44, v45
	v_max3_f32 v0, v0, v46, v47
	v_max3_f32 v0, v0, v48, v49
	v_max3_f32 v0, v0, v18, v19
	v_max3_f32 v0, v0, v20, v21
	v_max3_f32 v0, v0, v22, v23
	v_max3_f32 v0, v0, v24, v25
	v_max3_f32 v0, v0, v26, v27
	v_max3_f32 v0, v0, v28, v29
	v_max3_f32 v0, v0, v30, v31
	v_max3_f32 v0, v0, v32, v33
	v_max3_f32 v0, v0, v2, v3
	v_max3_f32 v0, v0, v4, v5
	v_max3_f32 v0, v0, v6, v7
	v_max3_f32 v0, v0, v8, v9
	v_max3_f32 v0, v0, v10, v11
	v_max3_f32 v0, v0, v12, v13
	v_max3_f32 v0, v0, v14, v15
	v_max3_f32 v0, v0, v16, v17
	v_mov_b32_e32 v82, v0
	s_nop 1
	v_permlane32_swap_b32_e32 v0, v82
	v_max_f32_e32 v82, v82, v82
	v_max_f32_e32 v0, v0, v0
	v_max_f32_e32 v0, v0, v82
	v_sub_f32_e32 v79, v79, v0
	v_sub_f32_e32 v78, v78, v0
	v_sub_f32_e32 v73, v73, v0
	v_sub_f32_e32 v72, v72, v0
	v_sub_f32_e32 v67, v67, v0
	v_sub_f32_e32 v66, v66, v0
	v_sub_f32_e32 v77, v77, v0
	v_sub_f32_e32 v76, v76, v0
	v_sub_f32_e32 v75, v75, v0
	v_sub_f32_e32 v74, v74, v0
	v_sub_f32_e32 v71, v71, v0
	v_sub_f32_e32 v70, v70, v0
	v_sub_f32_e32 v69, v69, v0
	v_sub_f32_e32 v68, v68, v0
	v_exp_f32_e32 v106, v66
	v_exp_f32_e32 v107, v67
	v_exp_f32_e32 v112, v72
	v_exp_f32_e32 v113, v73
	v_exp_f32_e32 v100, v78
	v_exp_f32_e32 v101, v79
	v_sub_f32_e32 v63, v63, v0
	v_sub_f32_e32 v62, v62, v0
	v_sub_f32_e32 v57, v57, v0
	v_sub_f32_e32 v56, v56, v0
	v_sub_f32_e32 v51, v51, v0
	v_sub_f32_e32 v50, v50, v0
	v_exp_f32_e32 v108, v68
	v_exp_f32_e32 v109, v69
	v_exp_f32_e32 v110, v70
	v_exp_f32_e32 v111, v71
	v_exp_f32_e32 v92, v74
	v_exp_f32_e32 v93, v75
	v_exp_f32_e32 v96, v76
	v_exp_f32_e32 v97, v77
	v_sub_f32_e32 v61, v61, v0
	v_sub_f32_e32 v60, v60, v0
	v_sub_f32_e32 v59, v59, v0
	v_sub_f32_e32 v58, v58, v0
	v_sub_f32_e32 v55, v55, v0
	v_sub_f32_e32 v54, v54, v0
	v_sub_f32_e32 v53, v53, v0
	v_sub_f32_e32 v52, v52, v0
	v_exp_f32_e32 v90, v50
	v_exp_f32_e32 v91, v51
	v_exp_f32_e32 v102, v56
	v_exp_f32_e32 v103, v57
	v_exp_f32_e32 v86, v62
	v_exp_f32_e32 v87, v63
	v_exp_f32_e32 v94, v52
	v_exp_f32_e32 v95, v53
	v_exp_f32_e32 v98, v54
	v_exp_f32_e32 v99, v55
	v_exp_f32_e32 v82, v58
	v_exp_f32_e32 v83, v59
	v_exp_f32_e32 v84, v60
	v_exp_f32_e32 v85, v61
	v_sub_f32_e32 v81, v81, v0
	v_sub_f32_e32 v80, v80, v0
	v_exp_f32_e32 v104, v80
	v_exp_f32_e32 v105, v81
	v_pk_add_f32 v[68:69], v[112:113], 0 op_sel_hi:[1,0]
	v_pk_add_f32 v[70:71], v[100:101], 0 op_sel_hi:[1,0]
	v_pk_add_f32 v[80:81], v[106:107], 0 op_sel_hi:[1,0]
	v_sub_f32_e32 v65, v65, v0
	v_sub_f32_e32 v64, v64, v0
	v_sub_f32_e32 v47, v47, v0
	v_sub_f32_e32 v46, v46, v0
	v_sub_f32_e32 v45, v45, v0
	v_sub_f32_e32 v44, v44, v0
	v_sub_f32_e32 v43, v43, v0
	v_sub_f32_e32 v42, v42, v0
	v_sub_f32_e32 v41, v41, v0
	v_sub_f32_e32 v40, v40, v0
	v_pk_add_f32 v[72:73], v[110:111], 0 op_sel_hi:[1,0]
	v_pk_add_f32 v[74:75], v[96:97], 0 op_sel_hi:[1,0]
	v_pk_add_f32 v[76:77], v[108:109], 0 op_sel_hi:[1,0]
	v_pk_add_f32 v[78:79], v[92:93], 0 op_sel_hi:[1,0]
	v_exp_f32_e32 v88, v64
	v_exp_f32_e32 v89, v65
	v_pk_add_f32 v[50:51], v[90:91], v[80:81]
	v_pk_add_f32 v[62:63], v[86:87], v[70:71]
	v_pk_add_f32 v[70:71], v[102:103], v[68:69]
	v_sub_f32_e32 v49, v49, v0
	v_sub_f32_e32 v48, v48, v0
	v_sub_f32_e32 v39, v39, v0
	v_sub_f32_e32 v38, v38, v0
	v_sub_f32_e32 v37, v37, v0
	v_sub_f32_e32 v36, v36, v0
	v_sub_f32_e32 v35, v35, v0
	v_sub_f32_e32 v34, v34, v0
	v_exp_f32_e32 v80, v40
	v_exp_f32_e32 v81, v41
	v_exp_f32_e32 v60, v42
	v_exp_f32_e32 v61, v43
	v_exp_f32_e32 v64, v44
	v_exp_f32_e32 v65, v45
	v_exp_f32_e32 v68, v46
	v_exp_f32_e32 v69, v47
	v_pk_add_f32 v[52:53], v[82:83], v[78:79]
	v_pk_add_f32 v[54:55], v[94:95], v[76:77]
	v_pk_add_f32 v[56:57], v[84:85], v[74:75]
	v_pk_add_f32 v[58:59], v[98:99], v[72:73]
	v_exp_f32_e32 v74, v34
	v_exp_f32_e32 v75, v35
	v_exp_f32_e32 v76, v36
	v_exp_f32_e32 v77, v37
	v_exp_f32_e32 v78, v38
	v_exp_f32_e32 v79, v39
	v_exp_f32_e32 v72, v48
	v_exp_f32_e32 v73, v49
	v_pk_add_f32 v[66:67], v[104:105], 0 op_sel_hi:[1,0]
	v_sub_f32_e32 v33, v33, v0
	v_sub_f32_e32 v32, v32, v0
	v_sub_f32_e32 v29, v29, v0
	v_sub_f32_e32 v28, v28, v0
	v_sub_f32_e32 v25, v25, v0
	v_sub_f32_e32 v24, v24, v0
	v_sub_f32_e32 v21, v21, v0
	v_sub_f32_e32 v20, v20, v0
	v_pk_add_f32 v[66:67], v[88:89], v[66:67]
	v_pk_add_f32 v[36:37], v[80:81], v[70:71]
	v_pk_add_f32 v[38:39], v[68:69], v[62:63]
	v_pk_add_f32 v[42:43], v[64:65], v[56:57]
	v_pk_add_f32 v[46:47], v[60:61], v[52:53]
	v_sub_f32_e32 v31, v31, v0
	v_sub_f32_e32 v30, v30, v0
	v_sub_f32_e32 v27, v27, v0
	v_sub_f32_e32 v26, v26, v0
	v_sub_f32_e32 v23, v23, v0
	v_sub_f32_e32 v22, v22, v0
	v_sub_f32_e32 v19, v19, v0
	v_sub_f32_e32 v18, v18, v0
	v_exp_f32_e32 v62, v20
	v_exp_f32_e32 v63, v21
	v_exp_f32_e32 v70, v24
	v_exp_f32_e32 v71, v25
	v_exp_f32_e32 v52, v28
	v_exp_f32_e32 v53, v29
	v_exp_f32_e32 v56, v32
	v_exp_f32_e32 v57, v33
	v_pk_add_f32 v[34:35], v[72:73], v[66:67]
	v_pk_add_f32 v[40:41], v[78:79], v[58:59]
	v_pk_add_f32 v[44:45], v[76:77], v[54:55]
	v_pk_add_f32 v[48:49], v[74:75], v[50:51]
	v_exp_f32_e32 v58, v18
	v_exp_f32_e32 v59, v19
	v_exp_f32_e32 v66, v22
	v_exp_f32_e32 v67, v23
	v_exp_f32_e32 v50, v26
	v_exp_f32_e32 v51, v27
	v_exp_f32_e32 v54, v30
	v_exp_f32_e32 v55, v31
	v_sub_f32_e32 v13, v13, v0
	v_sub_f32_e32 v12, v12, v0
	v_sub_f32_e32 v11, v11, v0
	v_sub_f32_e32 v10, v10, v0
	v_sub_f32_e32 v5, v5, v0
	v_sub_f32_e32 v4, v4, v0
	v_sub_f32_e32 v3, v3, v0
	v_sub_f32_e32 v2, v2, v0
	v_pk_add_f32 v[22:23], v[62:63], v[44:45]
	v_pk_add_f32 v[24:25], v[52:53], v[42:43]
	v_pk_add_f32 v[30:31], v[70:71], v[36:37]
	v_pk_add_f32 v[32:33], v[56:57], v[34:35]
	v_sub_f32_e32 v17, v17, v0
	v_sub_f32_e32 v16, v16, v0
	v_sub_f32_e32 v15, v15, v0
	v_sub_f32_e32 v14, v14, v0
	v_sub_f32_e32 v9, v9, v0
	v_sub_f32_e32 v8, v8, v0
	v_sub_f32_e32 v7, v7, v0
	v_sub_f32_e32 v6, v6, v0
	v_exp_f32_e32 v42, v2
	v_exp_f32_e32 v43, v3
	v_exp_f32_e32 v44, v4
	v_exp_f32_e32 v45, v5
	v_exp_f32_e32 v34, v10
	v_exp_f32_e32 v35, v11
	v_exp_f32_e32 v36, v12
	v_exp_f32_e32 v37, v13
	v_pk_add_f32 v[18:19], v[58:59], v[48:49]
	v_pk_add_f32 v[20:21], v[50:51], v[46:47]
	v_pk_add_f32 v[26:27], v[66:67], v[40:41]
	v_pk_add_f32 v[28:29], v[54:55], v[38:39]
	v_exp_f32_e32 v46, v6
	v_exp_f32_e32 v47, v7
	v_exp_f32_e32 v48, v8
	v_exp_f32_e32 v49, v9
	v_exp_f32_e32 v38, v14
	v_exp_f32_e32 v39, v15
	v_exp_f32_e32 v40, v16
	v_exp_f32_e32 v41, v17
	v_pk_add_f32 v[10:11], v[36:37], v[24:25]
	v_pk_add_f32 v[12:13], v[44:45], v[22:23]
	v_pk_add_f32 v[14:15], v[34:35], v[20:21]
	v_pk_add_f32 v[16:17], v[42:43], v[18:19]
	v_pk_add_f32 v[2:3], v[40:41], v[32:33]
	v_pk_add_f32 v[4:5], v[48:49], v[30:31]
	v_pk_add_f32 v[6:7], v[38:39], v[28:29]
	v_pk_add_f32 v[8:9], v[46:47], v[26:27]
	v_add_f32_e32 v14, v16, v14
	v_add_f32_e32 v15, v17, v15
	v_add_f32_e32 v10, v12, v10
	v_add_f32_e32 v11, v13, v11
	v_add_f32_e32 v6, v8, v6
	v_add_f32_e32 v7, v9, v7
	v_add_f32_e32 v2, v4, v2
	v_add_f32_e32 v3, v5, v3
	v_add_f32_e32 v4, v14, v15
	v_add_f32_e32 v5, v10, v11
	v_add_f32_e32 v4, v4, v5
	v_add_f32_e32 v5, v6, v7
	v_add_f32_e32 v2, v2, v3
	v_add_f32_e32 v2, v5, v2
	v_add_f32_e32 v187, v4, v2
	v_cvt_pk_bf16_f32 v18, v106, v107
	v_cvt_pk_bf16_f32 v19, v108, v109
	v_cvt_pk_bf16_f32 v20, v110, v111
	v_cvt_pk_bf16_f32 v21, v112, v113
	ds_read_b64_tr_b16 v[2:3], v185 offset:36864
	ds_read_b64_tr_b16 v[4:5], v185 offset:38016
	s_waitcnt lgkmcnt(0)
	v_mfma_f32_32x32x16_bf16 v[2:17], v[18:21], v[2:5], 0
	ds_read_b64_tr_b16 v[22:23], v185 offset:36928
	ds_read_b64_tr_b16 v[24:25], v185 offset:38080
	v_cvt_pk_bf16_f32 v106, v92, v93
	v_cvt_pk_bf16_f32 v107, v96, v97
	v_cvt_pk_bf16_f32 v108, v100, v101
	v_cvt_pk_bf16_f32 v109, v104, v105
	ds_read_b64_tr_b16 v[110:111], v185 offset:39168
	ds_read_b64_tr_b16 v[112:113], v185 offset:40320
	v_cvt_pk_bf16_f32 v90, v90, v91
	s_waitcnt lgkmcnt(2)
	v_mfma_f32_32x32x16_bf16 v[18:33], v[18:21], v[22:25], 0
	v_cvt_pk_bf16_f32 v91, v94, v95
	v_cvt_pk_bf16_f32 v92, v98, v99
	v_cvt_pk_bf16_f32 v93, v102, v103
	v_cvt_pk_bf16_f32 v82, v82, v83
	v_cvt_pk_bf16_f32 v83, v84, v85
	v_cvt_pk_bf16_f32 v84, v86, v87
	v_cvt_pk_bf16_f32 v85, v88, v89
	s_waitcnt lgkmcnt(0)
	v_mfma_f32_32x32x16_bf16 v[2:17], v[106:109], v[110:113], v[2:17]
	ds_read_b64_tr_b16 v[110:111], v185 offset:39232
	ds_read_b64_tr_b16 v[112:113], v185 offset:40384
	ds_read_b64_tr_b16 v[94:95], v185 offset:41472
	ds_read_b64_tr_b16 v[96:97], v185 offset:42624
	v_cvt_pk_bf16_f32 v74, v74, v75
	v_cvt_pk_bf16_f32 v75, v76, v77
	v_cvt_pk_bf16_f32 v76, v78, v79
	v_cvt_pk_bf16_f32 v77, v80, v81
	v_cvt_pk_bf16_f32 v58, v58, v59
	s_waitcnt lgkmcnt(2)
	v_mfma_f32_32x32x16_bf16 v[18:33], v[106:109], v[110:113], v[18:33]
	v_cvt_pk_bf16_f32 v59, v62, v63
	v_cvt_pk_bf16_f32 v50, v50, v51
	v_cvt_pk_bf16_f32 v51, v52, v53
	v_cvt_pk_bf16_f32 v52, v54, v55
	v_cvt_pk_bf16_f32 v53, v56, v57
	v_cvt_pk_bf16_f32 v42, v42, v43
	v_cvt_pk_bf16_f32 v43, v44, v45
	s_waitcnt lgkmcnt(0)
	v_mfma_f32_32x32x16_bf16 v[2:17], v[90:93], v[94:97], v[2:17]
	ds_read_b64_tr_b16 v[94:95], v185 offset:41536
	ds_read_b64_tr_b16 v[96:97], v185 offset:42688
	ds_read_b64_tr_b16 v[86:87], v185 offset:43776
	ds_read_b64_tr_b16 v[88:89], v185 offset:44928
	v_cvt_pk_bf16_f32 v44, v46, v47
	v_cvt_pk_bf16_f32 v45, v48, v49
	v_cvt_pk_bf16_f32 v34, v34, v35
	v_cvt_pk_bf16_f32 v35, v36, v37
	v_cvt_pk_bf16_f32 v36, v38, v39
	s_waitcnt lgkmcnt(2)
	v_mfma_f32_32x32x16_bf16 v[18:33], v[90:93], v[94:97], v[18:33]
	v_cvt_pk_bf16_f32 v37, v40, v41
	v_mov_b32_e32 v188, v187
	s_nop 1
	v_permlane32_swap_b32_e32 v187, v188
	s_waitcnt lgkmcnt(0)
	v_mfma_f32_32x32x16_bf16 v[2:17], v[82:85], v[86:89], v[2:17]
	ds_read_b64_tr_b16 v[86:87], v185 offset:43840
	ds_read_b64_tr_b16 v[88:89], v185 offset:44992
	ds_read_b64_tr_b16 v[78:79], v185 offset:46080
	ds_read_b64_tr_b16 v[80:81], v185 offset:47232
	s_waitcnt lgkmcnt(2)
	v_mfma_f32_32x32x16_bf16 v[18:33], v[82:85], v[86:89], v[18:33]
	s_waitcnt lgkmcnt(0)
	v_mfma_f32_32x32x16_bf16 v[2:17], v[74:77], v[78:81], v[2:17]
	ds_read_b64_tr_b16 v[78:79], v185 offset:46144
	ds_read_b64_tr_b16 v[80:81], v185 offset:47296
	s_waitcnt lgkmcnt(0)
	v_mfma_f32_32x32x16_bf16 v[18:33], v[74:77], v[78:81], v[18:33]
	v_cvt_pk_bf16_f32 v74, v60, v61
	v_cvt_pk_bf16_f32 v75, v64, v65
	v_cvt_pk_bf16_f32 v76, v68, v69
	v_cvt_pk_bf16_f32 v77, v72, v73
	ds_read_b64_tr_b16 v[78:79], v185 offset:48384
	ds_read_b64_tr_b16 v[80:81], v185 offset:49536
	v_cvt_pk_bf16_f32 v60, v66, v67
	v_cvt_pk_bf16_f32 v61, v70, v71
	s_waitcnt lgkmcnt(0)
	v_mfma_f32_32x32x16_bf16 v[2:17], v[74:77], v[78:81], v[2:17]
	ds_read_b64_tr_b16 v[78:79], v185 offset:48448
	ds_read_b64_tr_b16 v[80:81], v185 offset:49600
	ds_read_b64_tr_b16 v[62:63], v185 offset:50688
	ds_read_b64_tr_b16 v[64:65], v185 offset:51840
	s_waitcnt lgkmcnt(2)
	v_mfma_f32_32x32x16_bf16 v[18:33], v[74:77], v[78:81], v[18:33]
	s_waitcnt lgkmcnt(0)
	v_mfma_f32_32x32x16_bf16 v[2:17], v[58:61], v[62:65], v[2:17]
	ds_read_b64_tr_b16 v[62:63], v185 offset:50752
	ds_read_b64_tr_b16 v[64:65], v185 offset:51904
	ds_read_b64_tr_b16 v[54:55], v185 offset:52992
	ds_read_b64_tr_b16 v[56:57], v185 offset:54144
	s_waitcnt lgkmcnt(2)
	v_mfma_f32_32x32x16_bf16 v[18:33], v[58:61], v[62:65], v[18:33]
	s_waitcnt lgkmcnt(0)
	v_mfma_f32_32x32x16_bf16 v[2:17], v[50:53], v[54:57], v[2:17]
	ds_read_b64_tr_b16 v[54:55], v185 offset:53056
	ds_read_b64_tr_b16 v[56:57], v185 offset:54208
	ds_read_b64_tr_b16 v[46:47], v185 offset:55296
	ds_read_b64_tr_b16 v[48:49], v185 offset:56448
	s_waitcnt lgkmcnt(2)
	v_mfma_f32_32x32x16_bf16 v[18:33], v[50:53], v[54:57], v[18:33]
	s_waitcnt lgkmcnt(0)
	v_mfma_f32_32x32x16_bf16 v[2:17], v[42:45], v[46:49], v[2:17]
	ds_read_b64_tr_b16 v[46:47], v185 offset:55360
	ds_read_b64_tr_b16 v[48:49], v185 offset:56512
	ds_read_b64_tr_b16 v[38:39], v185 offset:57600
	ds_read_b64_tr_b16 v[40:41], v185 offset:58752
	s_waitcnt lgkmcnt(2)
	v_mfma_f32_32x32x16_bf16 v[18:33], v[42:45], v[46:49], v[18:33]
	s_waitcnt lgkmcnt(0)
	v_mfma_f32_32x32x16_bf16 v[2:17], v[34:37], v[38:41], v[2:17]
	ds_read_b64_tr_b16 v[38:39], v185 offset:57664
	ds_read_b64_tr_b16 v[40:41], v185 offset:58816
	s_waitcnt lgkmcnt(0)
	v_mfma_f32_32x32x16_bf16 v[18:33], v[34:37], v[38:41], v[18:33]
	v_add_f32_e32 v34, v187, v188
	s_and_saveexec_b64 s[2:3], s[44:45]
	s_cbranch_execz .LBB0_525
	v_div_scale_f32 v35, s[20:21], v34, v34, 1.0
	v_rcp_f32_e32 v36, v35
	v_div_scale_f32 v37, vcc, 1.0, v34, 1.0
	v_fma_f32 v38, -v35, v36, 1.0
	v_fmac_f32_e32 v36, v38, v36
	v_mul_f32_e32 v38, v37, v36
	v_fma_f32 v39, -v35, v38, v37
	v_fmac_f32_e32 v38, v39, v36
	v_fma_f32 v35, -v35, v38, v37
	v_div_fmas_f32 v35, v35, v36, v38
	v_div_fixup_f32 v35, v35, v34, 1.0
	ds_write_b32 v193, v35

.LBB0_534:
	v_cndmask_b32_e64 v81, v33, v208, s[6:7]
	v_cndmask_b32_e64 v80, v32, v208, s[6:7]
	v_cndmask_b32_e64 v79, v31, v208, s[6:7]
	v_cndmask_b32_e64 v78, v30, v208, s[6:7]
	v_cndmask_b32_e64 v77, v29, v208, s[6:7]
	v_cndmask_b32_e64 v76, v28, v208, s[6:7]
	v_cndmask_b32_e64 v75, v27, v208, s[6:7]
	v_cndmask_b32_e64 v74, v26, v208, s[6:7]
	v_cndmask_b32_e64 v73, v25, v208, s[6:7]
	v_cndmask_b32_e64 v72, v24, v208, s[6:7]
	v_cndmask_b32_e64 v71, v23, v208, s[6:7]
	v_cndmask_b32_e64 v70, v22, v208, s[6:7]
	v_cndmask_b32_e64 v69, v21, v208, s[6:7]
	v_cndmask_b32_e64 v68, v20, v208, s[6:7]
	v_cndmask_b32_e64 v67, v19, v208, s[6:7]
	v_cndmask_b32_e64 v66, v18, v208, s[6:7]
	v_cndmask_b32_e64 v49, v17, v208, s[8:9]
	v_cndmask_b32_e64 v48, v16, v208, s[8:9]
	v_cndmask_b32_e64 v47, v15, v208, s[8:9]
	v_cndmask_b32_e64 v46, v14, v208, s[8:9]
	v_cndmask_b32_e64 v45, v13, v208, s[8:9]
	v_cndmask_b32_e64 v44, v12, v208, s[8:9]
	v_cndmask_b32_e64 v43, v11, v208, s[8:9]
	v_cndmask_b32_e64 v42, v10, v208, s[8:9]
	v_cndmask_b32_e64 v41, v9, v208, s[8:9]
	v_cndmask_b32_e64 v40, v8, v208, s[8:9]
	v_cndmask_b32_e64 v39, v7, v208, s[8:9]
	v_cndmask_b32_e64 v38, v6, v208, s[8:9]
	v_cndmask_b32_e64 v37, v5, v208, s[8:9]
	v_cndmask_b32_e64 v36, v4, v208, s[8:9]
	v_cndmask_b32_e64 v35, v3, v208, s[8:9]
	v_cndmask_b32_e64 v34, v2, v208, s[8:9]
	v_cndmask_b32_e64 v33, v97, v208, s[10:11]
	v_cndmask_b32_e64 v32, v96, v208, s[10:11]
	v_cndmask_b32_e64 v31, v95, v208, s[10:11]
	v_cndmask_b32_e64 v30, v94, v208, s[10:11]
	v_cndmask_b32_e64 v29, v93, v208, s[10:11]
	v_cndmask_b32_e64 v28, v92, v208, s[10:11]
	v_cndmask_b32_e64 v27, v91, v208, s[10:11]
	v_cndmask_b32_e64 v26, v90, v208, s[10:11]
	v_cndmask_b32_e64 v25, v89, v208, s[10:11]
	v_cndmask_b32_e64 v24, v88, v208, s[10:11]
	v_cndmask_b32_e64 v23, v87, v208, s[10:11]
	v_cndmask_b32_e64 v22, v86, v208, s[10:11]
	v_cndmask_b32_e64 v21, v85, v208, s[10:11]
	v_cndmask_b32_e64 v20, v84, v208, s[10:11]
	v_cndmask_b32_e64 v19, v83, v208, s[10:11]
	v_cndmask_b32_e64 v18, v82, v208, s[10:11]
	v_cndmask_b32_e64 v2, v98, v208, s[44:45]
	v_cndmask_b32_e64 v3, v208, v99, s[46:47]
	v_cndmask_b32_e64 v4, v100, v208, s[48:49]
	v_cndmask_b32_e64 v5, v101, v208, s[50:51]
	v_cndmask_b32_e64 v6, v102, v208, s[76:77]
	v_cndmask_b32_e64 v7, v103, v208, s[78:79]
	v_cndmask_b32_e64 v8, v104, v208, s[80:81]
	v_cndmask_b32_e64 v9, v105, v208, s[82:83]
	v_cndmask_b32_e64 v10, v106, v208, s[84:85]
	v_cndmask_b32_e64 v11, v107, v208, s[86:87]
	v_cndmask_b32_e64 v12, v108, v208, s[88:89]
	v_cndmask_b32_e64 v13, v109, v208, s[90:91]
	v_cndmask_b32_e64 v14, v110, v208, s[92:93]
	v_cndmask_b32_e64 v15, v111, v208, s[94:95]
	v_cndmask_b32_e64 v16, v112, v208, s[96:97]
	v_cndmask_b32_e64 v17, v113, v208, s[38:39]
	s_nop 12
	v_mul_f32_e32 v0, 0x3fb8aa3b, v0
	v_max3_f32 v82, v208, v50, v51
	v_max3_f32 v82, v82, v52, v53
	v_max3_f32 v82, v82, v54, v55
	v_max3_f32 v82, v82, v56, v57
	v_max3_f32 v82, v82, v58, v59
	v_max3_f32 v82, v82, v60, v61
	v_max3_f32 v82, v82, v62, v63
	v_max3_f32 v82, v82, v64, v65
	v_max3_f32 v82, v82, v66, v67
	v_max3_f32 v82, v82, v68, v69
	v_max3_f32 v82, v82, v70, v71
	v_max3_f32 v82, v82, v72, v73
	v_max3_f32 v82, v82, v74, v75
	v_max3_f32 v82, v82, v76, v77
	v_max3_f32 v82, v82, v78, v79
	v_max3_f32 v82, v82, v80, v81
	v_max3_f32 v82, v82, v34, v35
	v_max3_f32 v82, v82, v36, v37
	v_max3_f32 v82, v82, v38, v39
	v_max3_f32 v82, v82, v40, v41
	v_max3_f32 v82, v82, v42, v43
	v_max3_f32 v82, v82, v44, v45
	v_max3_f32 v82, v82, v46, v47
	v_max3_f32 v82, v82, v48, v49
	v_max3_f32 v82, v82, v18, v19
	v_max3_f32 v82, v82, v20, v21
	v_max3_f32 v82, v82, v22, v23
	v_max3_f32 v82, v82, v24, v25
	v_max3_f32 v82, v82, v26, v27
	v_max3_f32 v82, v82, v28, v29
	v_max3_f32 v82, v82, v30, v31
	v_max3_f32 v82, v82, v32, v33
	v_max3_f32 v82, v82, v2, v3
	v_max3_f32 v82, v82, v4, v5
	v_max3_f32 v82, v82, v6, v7
	v_max3_f32 v82, v82, v8, v9
	v_max3_f32 v82, v82, v10, v11
	v_max3_f32 v82, v82, v12, v13
	v_max3_f32 v82, v82, v14, v15
	v_max3_f32 v82, v82, v16, v17
	v_mov_b32_e32 v83, v82
	s_nop 1
	v_permlane32_swap_b32_e32 v82, v83
	v_max3_f32 v174, v82, v83, v0
	v_sub_f32_e32 v53, v53, v174
	v_sub_f32_e32 v52, v52, v174
	v_sub_f32_e32 v51, v51, v174
	v_sub_f32_e32 v50, v50, v174
	v_exp_f32_e32 v108, v52
	v_exp_f32_e32 v109, v53
	v_sub_f32_e32 v69, v69, v174
	v_sub_f32_e32 v68, v68, v174
	v_exp_f32_e32 v106, v50
	v_exp_f32_e32 v107, v51
	v_sub_f32_e32 v67, v67, v174
	v_sub_f32_e32 v66, v66, v174
	v_exp_f32_e32 v94, v68
	v_exp_f32_e32 v95, v69
	v_sub_f32_e32 v59, v59, v174
	v_sub_f32_e32 v58, v58, v174
	v_sub_f32_e32 v57, v57, v174
	v_sub_f32_e32 v56, v56, v174
	v_sub_f32_e32 v55, v55, v174
	v_sub_f32_e32 v54, v54, v174
	v_exp_f32_e32 v90, v66
	v_exp_f32_e32 v91, v67
	v_sub_f32_e32 v65, v65, v174
	v_sub_f32_e32 v64, v64, v174
	v_sub_f32_e32 v63, v63, v174
	v_sub_f32_e32 v62, v62, v174
	v_sub_f32_e32 v61, v61, v174
	v_sub_f32_e32 v60, v60, v174
	v_exp_f32_e32 v110, v54
	v_exp_f32_e32 v111, v55
	v_exp_f32_e32 v112, v56
	v_exp_f32_e32 v113, v57
	v_exp_f32_e32 v92, v58
	v_exp_f32_e32 v93, v59
	v_sub_f32_e32 v75, v75, v174
	v_sub_f32_e32 v74, v74, v174
	v_sub_f32_e32 v73, v73, v174
	v_sub_f32_e32 v72, v72, v174
	v_sub_f32_e32 v71, v71, v174
	v_sub_f32_e32 v70, v70, v174
	v_exp_f32_e32 v96, v60
	v_exp_f32_e32 v97, v61
	v_exp_f32_e32 v100, v62
	v_exp_f32_e32 v101, v63
	v_exp_f32_e32 v104, v64
	v_exp_f32_e32 v105, v65
	v_pk_add_f32 v[60:61], v[108:109], 0 op_sel_hi:[1,0]
	v_sub_f32_e32 v81, v81, v174
	v_sub_f32_e32 v80, v80, v174
	v_sub_f32_e32 v79, v79, v174
	v_sub_f32_e32 v78, v78, v174
	v_sub_f32_e32 v77, v77, v174
	v_sub_f32_e32 v76, v76, v174
	v_exp_f32_e32 v98, v70
	v_exp_f32_e32 v99, v71
	v_exp_f32_e32 v102, v72
	v_exp_f32_e32 v103, v73
	v_exp_f32_e32 v82, v74
	v_exp_f32_e32 v83, v75
	v_sub_f32_e32 v43, v43, v174
	v_sub_f32_e32 v42, v42, v174
	v_sub_f32_e32 v41, v41, v174
	v_sub_f32_e32 v40, v40, v174
	v_sub_f32_e32 v39, v39, v174
	v_sub_f32_e32 v38, v38, v174
	v_sub_f32_e32 v37, v37, v174
	v_sub_f32_e32 v36, v36, v174
	v_pk_add_f32 v[64:65], v[106:107], 0 op_sel_hi:[1,0]
	v_exp_f32_e32 v84, v76
	v_exp_f32_e32 v85, v77
	v_exp_f32_e32 v86, v78
	v_exp_f32_e32 v87, v79
	v_exp_f32_e32 v88, v80
	v_exp_f32_e32 v89, v81
	v_pk_add_f32 v[70:71], v[94:95], v[60:61]
	v_sub_f32_e32 v49, v49, v174
	v_sub_f32_e32 v48, v48, v174
	v_sub_f32_e32 v47, v47, v174
	v_sub_f32_e32 v46, v46, v174
	v_sub_f32_e32 v45, v45, v174
	v_sub_f32_e32 v44, v44, v174
	v_sub_f32_e32 v35, v35, v174
	v_sub_f32_e32 v34, v34, v174
	v_exp_f32_e32 v76, v36
	v_exp_f32_e32 v77, v37
	v_exp_f32_e32 v78, v38
	v_exp_f32_e32 v79, v39
	v_exp_f32_e32 v80, v40
	v_exp_f32_e32 v81, v41
	v_exp_f32_e32 v60, v42
	v_exp_f32_e32 v61, v43
	v_pk_add_f32 v[66:67], v[90:91], v[64:65]
	v_exp_f32_e32 v74, v34
	v_exp_f32_e32 v75, v35
	v_exp_f32_e32 v64, v44
	v_exp_f32_e32 v65, v45
	v_exp_f32_e32 v68, v46
	v_exp_f32_e32 v69, v47
	v_exp_f32_e32 v72, v48
	v_exp_f32_e32 v73, v49
	v_pk_add_f32 v[52:53], v[112:113], 0 op_sel_hi:[1,0]
	v_pk_add_f32 v[56:57], v[110:111], 0 op_sel_hi:[1,0]
	v_pk_add_f32 v[62:63], v[92:93], 0 op_sel_hi:[1,0]
	v_pk_add_f32 v[50:51], v[104:105], 0 op_sel_hi:[1,0]
	v_pk_add_f32 v[54:55], v[100:101], 0 op_sel_hi:[1,0]
	v_pk_add_f32 v[58:59], v[96:97], 0 op_sel_hi:[1,0]
	v_pk_add_f32 v[62:63], v[82:83], v[62:63]
	v_pk_add_f32 v[56:57], v[98:99], v[56:57]
	v_pk_add_f32 v[52:53], v[102:103], v[52:53]
	v_sub_f32_e32 v33, v33, v174
	v_sub_f32_e32 v32, v32, v174
	v_sub_f32_e32 v29, v29, v174
	v_sub_f32_e32 v28, v28, v174
	v_sub_f32_e32 v25, v25, v174
	v_sub_f32_e32 v24, v24, v174
	v_sub_f32_e32 v21, v21, v174
	v_sub_f32_e32 v20, v20, v174
	v_pk_add_f32 v[58:59], v[84:85], v[58:59]
	v_pk_add_f32 v[54:55], v[86:87], v[54:55]
	v_pk_add_f32 v[50:51], v[88:89], v[50:51]
	v_pk_add_f32 v[36:37], v[80:81], v[52:53]
	v_pk_add_f32 v[40:41], v[78:79], v[56:57]
	v_pk_add_f32 v[44:45], v[76:77], v[70:71]
	v_pk_add_f32 v[46:47], v[60:61], v[62:63]
	v_sub_f32_e32 v31, v31, v174
	v_sub_f32_e32 v30, v30, v174
	v_sub_f32_e32 v27, v27, v174
	v_sub_f32_e32 v26, v26, v174
	v_sub_f32_e32 v23, v23, v174
	v_sub_f32_e32 v22, v22, v174
	v_sub_f32_e32 v19, v19, v174
	v_sub_f32_e32 v18, v18, v174
	v_exp_f32_e32 v62, v20
	v_exp_f32_e32 v63, v21
	v_exp_f32_e32 v70, v24
	v_exp_f32_e32 v71, v25
	v_exp_f32_e32 v52, v28
	v_exp_f32_e32 v53, v29
	v_exp_f32_e32 v56, v32
	v_exp_f32_e32 v57, v33
	v_pk_add_f32 v[34:35], v[72:73], v[50:51]
	v_pk_add_f32 v[38:39], v[68:69], v[54:55]
	v_pk_add_f32 v[42:43], v[64:65], v[58:59]
	v_pk_add_f32 v[48:49], v[74:75], v[66:67]
	v_exp_f32_e32 v58, v18
	v_exp_f32_e32 v59, v19
	v_exp_f32_e32 v66, v22
	v_exp_f32_e32 v67, v23
	v_exp_f32_e32 v50, v26
	v_exp_f32_e32 v51, v27
	v_exp_f32_e32 v54, v30
	v_exp_f32_e32 v55, v31
	v_sub_f32_e32 v13, v13, v174
	v_sub_f32_e32 v12, v12, v174
	v_sub_f32_e32 v11, v11, v174
	v_sub_f32_e32 v10, v10, v174
	v_sub_f32_e32 v5, v5, v174
	v_sub_f32_e32 v4, v4, v174
	v_sub_f32_e32 v3, v3, v174
	v_sub_f32_e32 v2, v2, v174
	v_pk_add_f32 v[22:23], v[62:63], v[44:45]
	v_pk_add_f32 v[24:25], v[52:53], v[42:43]
	v_pk_add_f32 v[30:31], v[70:71], v[36:37]
	v_pk_add_f32 v[32:33], v[56:57], v[34:35]
	v_sub_f32_e32 v17, v17, v174
	v_sub_f32_e32 v16, v16, v174
	v_sub_f32_e32 v15, v15, v174
	v_sub_f32_e32 v14, v14, v174
	v_sub_f32_e32 v9, v9, v174
	v_sub_f32_e32 v8, v8, v174
	v_sub_f32_e32 v7, v7, v174
	v_sub_f32_e32 v6, v6, v174
	v_exp_f32_e32 v42, v2
	v_exp_f32_e32 v43, v3
	v_exp_f32_e32 v44, v4
	v_exp_f32_e32 v45, v5
	v_exp_f32_e32 v34, v10
	v_exp_f32_e32 v35, v11
	v_exp_f32_e32 v36, v12
	v_exp_f32_e32 v37, v13
	v_pk_add_f32 v[18:19], v[58:59], v[48:49]
	v_pk_add_f32 v[20:21], v[50:51], v[46:47]
	v_pk_add_f32 v[26:27], v[66:67], v[40:41]
	v_pk_add_f32 v[28:29], v[54:55], v[38:39]
	v_exp_f32_e32 v46, v6
	v_exp_f32_e32 v47, v7
	v_exp_f32_e32 v48, v8
	v_exp_f32_e32 v49, v9
	v_exp_f32_e32 v38, v14
	v_exp_f32_e32 v39, v15
	v_exp_f32_e32 v40, v16
	v_exp_f32_e32 v41, v17
	v_pk_add_f32 v[10:11], v[36:37], v[24:25]
	v_pk_add_f32 v[12:13], v[44:45], v[22:23]
	v_pk_add_f32 v[14:15], v[34:35], v[20:21]
	v_pk_add_f32 v[16:17], v[42:43], v[18:19]
	v_pk_add_f32 v[2:3], v[40:41], v[32:33]
	v_pk_add_f32 v[4:5], v[48:49], v[30:31]
	v_pk_add_f32 v[6:7], v[38:39], v[28:29]
	v_pk_add_f32 v[8:9], v[46:47], v[26:27]
	v_add_f32_e32 v14, v16, v14
	v_add_f32_e32 v15, v17, v15
	v_add_f32_e32 v10, v12, v10
	v_add_f32_e32 v11, v13, v11
	v_add_f32_e32 v6, v8, v6
	v_add_f32_e32 v7, v9, v7
	v_add_f32_e32 v2, v4, v2
	v_add_f32_e32 v3, v5, v3
	v_add_f32_e32 v4, v14, v15
	v_add_f32_e32 v5, v10, v11
	v_add_f32_e32 v4, v4, v5
	v_add_f32_e32 v5, v6, v7
	v_add_f32_e32 v2, v2, v3
	v_add_f32_e32 v2, v5, v2
	v_add_f32_e32 v175, v4, v2
	v_cvt_pk_bf16_f32 v18, v106, v107
	v_cvt_pk_bf16_f32 v19, v108, v109
	v_cvt_pk_bf16_f32 v20, v110, v111
	v_cvt_pk_bf16_f32 v21, v112, v113
	ds_read_b64_tr_b16 v[2:3], v173 offset:36864
	ds_read_b64_tr_b16 v[4:5], v173 offset:38016
	s_waitcnt lgkmcnt(0)
	v_mfma_f32_32x32x16_bf16 v[2:17], v[18:21], v[2:5], 0
	ds_read_b64_tr_b16 v[22:23], v173 offset:36928
	ds_read_b64_tr_b16 v[24:25], v173 offset:38080
	v_cvt_pk_bf16_f32 v106, v92, v93
	v_cvt_pk_bf16_f32 v107, v96, v97
	v_cvt_pk_bf16_f32 v108, v100, v101
	v_cvt_pk_bf16_f32 v109, v104, v105
	ds_read_b64_tr_b16 v[110:111], v173 offset:39168
	ds_read_b64_tr_b16 v[112:113], v173 offset:40320
	v_cvt_pk_bf16_f32 v90, v90, v91
	s_waitcnt lgkmcnt(2)
	v_mfma_f32_32x32x16_bf16 v[18:33], v[18:21], v[22:25], 0
	v_cvt_pk_bf16_f32 v91, v94, v95
	v_cvt_pk_bf16_f32 v92, v98, v99
	v_cvt_pk_bf16_f32 v93, v102, v103
	v_cvt_pk_bf16_f32 v82, v82, v83
	v_cvt_pk_bf16_f32 v83, v84, v85
	v_cvt_pk_bf16_f32 v84, v86, v87
	v_cvt_pk_bf16_f32 v85, v88, v89
	s_waitcnt lgkmcnt(0)
	v_mfma_f32_32x32x16_bf16 v[2:17], v[106:109], v[110:113], v[2:17]
	ds_read_b64_tr_b16 v[110:111], v173 offset:39232
	ds_read_b64_tr_b16 v[112:113], v173 offset:40384
	ds_read_b64_tr_b16 v[94:95], v173 offset:41472
	ds_read_b64_tr_b16 v[96:97], v173 offset:42624
	v_cvt_pk_bf16_f32 v74, v74, v75
	v_cvt_pk_bf16_f32 v75, v76, v77
	v_cvt_pk_bf16_f32 v76, v78, v79
	v_cvt_pk_bf16_f32 v77, v80, v81
	v_cvt_pk_bf16_f32 v58, v58, v59
	s_waitcnt lgkmcnt(2)
	v_mfma_f32_32x32x16_bf16 v[18:33], v[106:109], v[110:113], v[18:33]
	v_cvt_pk_bf16_f32 v59, v62, v63
	v_cvt_pk_bf16_f32 v50, v50, v51
	v_cvt_pk_bf16_f32 v51, v52, v53
	v_cvt_pk_bf16_f32 v52, v54, v55
	v_cvt_pk_bf16_f32 v53, v56, v57
	v_cvt_pk_bf16_f32 v42, v42, v43
	v_cvt_pk_bf16_f32 v43, v44, v45
	s_waitcnt lgkmcnt(0)
	v_mfma_f32_32x32x16_bf16 v[2:17], v[90:93], v[94:97], v[2:17]
	ds_read_b64_tr_b16 v[94:95], v173 offset:41536
	ds_read_b64_tr_b16 v[96:97], v173 offset:42688
	ds_read_b64_tr_b16 v[86:87], v173 offset:43776
	ds_read_b64_tr_b16 v[88:89], v173 offset:44928
	v_cvt_pk_bf16_f32 v44, v46, v47
	v_cvt_pk_bf16_f32 v45, v48, v49
	v_cvt_pk_bf16_f32 v34, v34, v35
	v_cvt_pk_bf16_f32 v35, v36, v37
	v_cvt_pk_bf16_f32 v36, v38, v39
	s_waitcnt lgkmcnt(2)
	v_mfma_f32_32x32x16_bf16 v[18:33], v[90:93], v[94:97], v[18:33]
	v_cvt_pk_bf16_f32 v37, v40, v41
	v_mov_b32_e32 v185, v175
	s_nop 1
	v_permlane32_swap_b32_e32 v175, v185
	s_waitcnt lgkmcnt(0)
	v_mfma_f32_32x32x16_bf16 v[2:17], v[82:85], v[86:89], v[2:17]
	ds_read_b64_tr_b16 v[86:87], v173 offset:43840
	ds_read_b64_tr_b16 v[88:89], v173 offset:44992
	ds_read_b64_tr_b16 v[78:79], v173 offset:46080
	ds_read_b64_tr_b16 v[80:81], v173 offset:47232
	s_waitcnt lgkmcnt(2)
	v_mfma_f32_32x32x16_bf16 v[18:33], v[82:85], v[86:89], v[18:33]
	s_waitcnt lgkmcnt(0)
	v_mfma_f32_32x32x16_bf16 v[2:17], v[74:77], v[78:81], v[2:17]
	ds_read_b64_tr_b16 v[78:79], v173 offset:46144
	ds_read_b64_tr_b16 v[80:81], v173 offset:47296
	s_waitcnt lgkmcnt(0)
	v_mfma_f32_32x32x16_bf16 v[18:33], v[74:77], v[78:81], v[18:33]
	v_cvt_pk_bf16_f32 v74, v60, v61
	v_cvt_pk_bf16_f32 v75, v64, v65
	v_cvt_pk_bf16_f32 v76, v68, v69
	v_cvt_pk_bf16_f32 v77, v72, v73
	ds_read_b64_tr_b16 v[78:79], v173 offset:48384
	ds_read_b64_tr_b16 v[80:81], v173 offset:49536
	v_cvt_pk_bf16_f32 v60, v66, v67
	v_cvt_pk_bf16_f32 v61, v70, v71
	s_waitcnt lgkmcnt(0)
	v_mfma_f32_32x32x16_bf16 v[2:17], v[74:77], v[78:81], v[2:17]
	ds_read_b64_tr_b16 v[78:79], v173 offset:48448
	ds_read_b64_tr_b16 v[80:81], v173 offset:49600
	ds_read_b64_tr_b16 v[62:63], v173 offset:50688
	ds_read_b64_tr_b16 v[64:65], v173 offset:51840
	s_waitcnt lgkmcnt(2)
	v_mfma_f32_32x32x16_bf16 v[18:33], v[74:77], v[78:81], v[18:33]
	s_waitcnt lgkmcnt(0)
	v_mfma_f32_32x32x16_bf16 v[2:17], v[58:61], v[62:65], v[2:17]
	ds_read_b64_tr_b16 v[62:63], v173 offset:50752
	ds_read_b64_tr_b16 v[64:65], v173 offset:51904
	ds_read_b64_tr_b16 v[54:55], v173 offset:52992
	ds_read_b64_tr_b16 v[56:57], v173 offset:54144
	s_waitcnt lgkmcnt(2)
	v_mfma_f32_32x32x16_bf16 v[18:33], v[58:61], v[62:65], v[18:33]
	s_waitcnt lgkmcnt(0)
	v_mfma_f32_32x32x16_bf16 v[2:17], v[50:53], v[54:57], v[2:17]
	ds_read_b64_tr_b16 v[54:55], v173 offset:53056
	ds_read_b64_tr_b16 v[56:57], v173 offset:54208
	ds_read_b64_tr_b16 v[46:47], v173 offset:55296
	ds_read_b64_tr_b16 v[48:49], v173 offset:56448
	s_waitcnt lgkmcnt(2)
	v_mfma_f32_32x32x16_bf16 v[18:33], v[50:53], v[54:57], v[18:33]
	s_waitcnt lgkmcnt(0)
	v_mfma_f32_32x32x16_bf16 v[2:17], v[42:45], v[46:49], v[2:17]
	ds_read_b64_tr_b16 v[46:47], v173 offset:55360
	ds_read_b64_tr_b16 v[48:49], v173 offset:56512
	ds_read_b64_tr_b16 v[38:39], v173 offset:57600
	ds_read_b64_tr_b16 v[40:41], v173 offset:58752
	s_waitcnt lgkmcnt(2)
	v_mfma_f32_32x32x16_bf16 v[18:33], v[42:45], v[46:49], v[18:33]
	s_waitcnt lgkmcnt(0)
	v_mfma_f32_32x32x16_bf16 v[2:17], v[34:37], v[38:41], v[2:17]
	ds_read_b64_tr_b16 v[38:39], v173 offset:57664
	ds_read_b64_tr_b16 v[40:41], v173 offset:58816
	s_waitcnt lgkmcnt(0)
	v_mfma_f32_32x32x16_bf16 v[18:33], v[34:37], v[38:41], v[18:33]
	s_and_saveexec_b64 s[2:3], s[4:5]
	s_cbranch_execz .LBB0_531
	v_sub_f32_e32 v0, v0, v174
	v_exp_f32_e32 v0, v0
	v_add_f32_e32 v34, v175, v185
	v_add_f32_e32 v0, v34, v0
	v_div_scale_f32 v34, s[16:17], v0, v0, 1.0
	v_rcp_f32_e32 v35, v34
	v_div_scale_f32 v36, vcc, 1.0, v0, 1.0
	v_fma_f32 v37, -v34, v35, 1.0
	v_fmac_f32_e32 v35, v37, v35
	v_mul_f32_e32 v37, v36, v35
	v_fma_f32 v38, -v34, v37, v36
	v_fmac_f32_e32 v37, v38, v35
	v_fma_f32 v34, -v34, v37, v36
	v_div_fmas_f32 v34, v34, v35, v37
	v_div_fixup_f32 v0, v34, v0, 1.0
	ds_write_b32 v193, v0
	s_branch .LBB0_531

.LBB0_615:
	s_and_b32 s30, s5, 1
	s_mul_i32 s31, s30, 0x8800
	v_mov_b64_e32 v[126:127], v[94:95]
	v_add_u32_e32 v0, s31, v194
	ds_read_b128 v[2:5], v0 offset:0
	ds_read_b128 v[8:11], v0 offset:32
	ds_read_b128 v[12:15], v0 offset:64
	ds_read_b128 v[200:203], v0 offset:0x60
	ds_read_b128 v[212:215], v0 offset:0x80
	ds_read_b128 v[216:219], v0 offset:0xa0
	ds_read_b128 v[220:223], v0 offset:0xc0
	ds_read_b128 v[224:227], v0 offset:0xe0
	ds_read_b128 v[228:231], v0 offset:0x2200
	v_mov_b64_e32 v[124:125], v[92:93]
	v_mov_b64_e32 v[122:123], v[90:91]
	v_mov_b64_e32 v[120:121], v[88:89]
	v_mov_b64_e32 v[118:119], v[86:87]
	v_mov_b64_e32 v[116:117], v[84:85]
	v_mov_b64_e32 v[114:115], v[82:83]
	v_mov_b64_e32 v[112:113], v[80:81]
	ds_read_b128 v[232:235], v0 offset:0x2220
	ds_read_b128 v[236:239], v0 offset:0x2240
	ds_read_b128 v[240:243], v0 offset:0x2260
	ds_read_b128 v[244:247], v0 offset:0x2280
	ds_read_b128 v[248:251], v0 offset:0x22a0
	ds_read_b128 v[180:183], v0 offset:0x22c0
	ds_read_b128 v[196:199], v0 offset:0x22e0
	s_waitcnt lgkmcnt(0)
	s_nop 0
	v_mfma_f32_32x32x16_bf16 v[96:111], v[2:5], v[128:131], v[80:95]
	v_mfma_f32_32x32x16_bf16 v[96:111], v[8:11], v[132:135], v[96:111]
	s_xor_b64 s[14:15], s[14:15], -1
	s_and_b64 vcc, exec, s[14:15]
	v_mfma_f32_32x32x16_bf16 v[112:127], v[228:231], v[128:131], v[112:127]
	v_mfma_f32_32x32x16_bf16 v[112:127], v[232:235], v[132:135], v[112:127]
	v_mfma_f32_32x32x16_bf16 v[96:111], v[12:15], v[136:139], v[96:111]
	v_mfma_f32_32x32x16_bf16 v[112:127], v[236:239], v[136:139], v[112:127]
	v_mfma_f32_32x32x16_bf16 v[96:111], v[200:203], v[140:143], v[96:111]
	v_mfma_f32_32x32x16_bf16 v[112:127], v[240:243], v[140:143], v[112:127]
	v_mfma_f32_32x32x16_bf16 v[96:111], v[212:215], v[144:147], v[96:111]
	v_mfma_f32_32x32x16_bf16 v[112:127], v[244:247], v[144:147], v[112:127]
	v_mfma_f32_32x32x16_bf16 v[96:111], v[216:219], v[148:151], v[96:111]
	v_mfma_f32_32x32x16_bf16 v[112:127], v[248:251], v[148:151], v[112:127]
	v_mfma_f32_32x32x16_bf16 v[96:111], v[220:223], v[152:155], v[96:111]
	v_mfma_f32_32x32x16_bf16 v[112:127], v[180:183], v[152:155], v[112:127]
	v_mfma_f32_32x32x16_bf16 v[96:111], v[224:227], v[156:159], v[96:111]
	v_mfma_f32_32x32x16_bf16 v[112:127], v[196:199], v[156:159], v[112:127]
	s_nop 12
	s_nop 0
	v_max3_f32 v0, v208, v96, v112
	v_max3_f32 v0, v0, v97, v113
	v_max3_f32 v0, v0, v98, v114
	v_max3_f32 v0, v0, v99, v115
	v_max3_f32 v0, v0, v100, v116
	v_max3_f32 v0, v0, v101, v117
	v_max3_f32 v0, v0, v102, v118
	v_max3_f32 v0, v0, v103, v119
	v_max3_f32 v0, v0, v104, v120
	v_max3_f32 v0, v0, v105, v121
	v_max3_f32 v0, v0, v106, v122
	v_max3_f32 v0, v0, v107, v123
	v_max3_f32 v0, v0, v108, v124
	v_max3_f32 v0, v0, v109, v125
	v_max3_f32 v0, v0, v110, v126
	v_max3_f32 v0, v0, v111, v127
	v_mov_b32_e32 v2, v0
	s_nop 1
	v_permlane32_swap_b32_e32 v0, v2
	v_max_f32_e32 v2, v2, v2
	v_max_f32_e32 v0, v0, v0
	v_max_f32_e32 v2, v0, v2
	s_cbranch_vccz .LBB0_659
	s_mov_b32 s2, 0x41000000
	v_cmp_lt_f32_e32 vcc, s2, v2
	s_mov_b64 s[18:19], 0
	s_mov_b64 s[16:17], 0
	s_cbranch_vccz .LBB0_618
	v_cndmask_b32_e32 v0, 0, v2, vcc
	s_mov_b64 s[16:17], -1
